# deferred weight conversion in the FFN-out phases reads the f32 weights with non-temporal loads (read once, do not displace the GEMM operands)
# speedup vs baseline: 1.0003x; 1.0003x over previous
.LBB0_71:
	s_waitcnt vmcnt(0)
	v_ashrrev_i32_e32 v22, 4, v132
	v_lshl_add_u32 v4, s11, 6, v22
	v_add_u32_e32 v0, 48, v4
	v_ashrrev_i32_e32 v1, 31, v0
	v_mul_lo_u32 v2, s4, v1
	v_mul_lo_u32 v3, s5, v0
	v_mad_u64_u32 v[0:1], s[8:9], s4, v0, 0
	v_add3_u32 v1, v1, v2, v3
	v_lshlrev_b32_e32 v2, 2, v132
	v_and_b32_e32 v18, 60, v2
	v_add_u32_e32 v2, 32, v4
	s_lshl_b32 s6, s7, 6
	v_ashrrev_i32_e32 v3, 31, v2
	s_ashr_i32 s7, s6, 31
	v_mul_lo_u32 v5, s4, v3
	v_mul_lo_u32 v6, s5, v2
	v_mad_u64_u32 v[2:3], s[8:9], s4, v2, 0
	v_lshl_add_u64 v[0:1], v[0:1], 2, s[0:1]
	s_lshl_b64 s[6:7], s[6:7], 2
	v_add3_u32 v3, v3, v5, v6
	v_lshl_add_u64 v[0:1], v[0:1], 0, s[6:7]
	v_lshlrev_b32_e32 v128, 2, v18
	v_lshl_add_u64 v[2:3], v[2:3], 2, s[0:1]
	v_lshl_add_u64 v[0:1], v[0:1], 0, v[128:129]
	v_lshl_add_u64 v[2:3], v[2:3], 0, s[6:7]
	v_lshl_add_u64 v[2:3], v[2:3], 0, v[128:129]
	global_load_dwordx4 v[12:15], v[0:1], off nt
	global_load_dwordx4 v[8:11], v[2:3], off nt
	v_add_u32_e32 v0, 16, v4
	v_ashrrev_i32_e32 v1, 31, v0
	v_mul_lo_u32 v2, s4, v1
	v_mul_lo_u32 v3, s5, v0
	v_mad_u64_u32 v[0:1], s[8:9], s4, v0, 0
	v_add3_u32 v1, v1, v2, v3
	v_ashrrev_i32_e32 v2, 31, v4
	v_mul_lo_u32 v5, s4, v2
	v_mul_lo_u32 v6, s5, v4
	v_mad_u64_u32 v[2:3], s[4:5], s4, v4, 0
	v_add3_u32 v3, v3, v5, v6
	v_lshl_add_u64 v[0:1], v[0:1], 2, s[0:1]
	v_lshl_add_u64 v[2:3], v[2:3], 2, s[0:1]
	v_lshl_add_u64 v[0:1], v[0:1], 0, s[6:7]
	v_lshl_add_u64 v[2:3], v[2:3], 0, s[6:7]
	v_lshl_add_u64 v[0:1], v[0:1], 0, v[128:129]
	v_lshl_add_u64 v[2:3], v[2:3], 0, v[128:129]
	global_load_dwordx4 v[4:7], v[0:1], off nt
	s_nop 0
	global_load_dwordx4 v[0:3], v[2:3], off nt
	s_movk_i32 s0, 0x104
	v_mad_u64_u32 v[16:17], s[0:1], v22, s0, v[128:129]
	v_lshlrev_b32_e32 v17, 3, v132
	v_and_b32_e32 v20, 56, v17
	v_add_u32_e32 v17, 0x100, v132
	v_ashrrev_i32_e32 v17, 3, v17
	v_ashrrev_i32_e32 v23, 3, v132
	v_lshlrev_b32_e32 v19, 2, v17
	v_mul_u32_u24_e32 v21, 0x104, v20
	v_lshlrev_b32_e32 v26, 2, v23
	v_and_b32_e32 v24, 15, v23
	v_and_b32_e32 v25, 15, v17
	v_lshlrev_b32_e32 v18, 2, v18
	v_lshlrev_b32_e32 v128, 1, v20
	v_add_u32_e32 v26, v26, v21
	v_add_u32_e32 v27, v19, v21
	s_branch .LBB0_74

.LBB0_87:
	v_lshl_add_u32 v10, s7, 6, v22
	v_ashrrev_i32_e32 v0, 31, v10
	v_add_u32_e32 v8, 32, v10
	v_mul_lo_u32 v2, s8, v0
	v_mul_lo_u32 v3, s9, v10
	v_mad_u64_u32 v[0:1], s[10:11], s8, v10, 0
	v_ashrrev_i32_e32 v9, 31, v8
	v_add3_u32 v1, v1, v2, v3
	v_add_u32_e32 v2, 16, v10
	v_mul_lo_u32 v11, s8, v9
	v_mul_lo_u32 v12, s9, v8
	v_mad_u64_u32 v[8:9], s[10:11], s8, v8, 0
	v_add_u32_e32 v10, 48, v10
	v_ashrrev_i32_e32 v3, 31, v2
	v_add3_u32 v9, v9, v11, v12
	v_ashrrev_i32_e32 v11, 31, v10
	s_lshl_b32 s6, s16, 6
	v_mul_lo_u32 v4, s8, v3
	v_mul_lo_u32 v5, s9, v2
	v_mad_u64_u32 v[2:3], s[10:11], s8, v2, 0
	v_mul_lo_u32 v12, s8, v11
	v_mul_lo_u32 v13, s9, v10
	v_mad_u64_u32 v[10:11], s[8:9], s8, v10, 0
	s_ashr_i32 s7, s6, 31
	v_add3_u32 v3, v3, v4, v5
	v_add3_u32 v11, v11, v12, v13
	v_lshl_add_u64 v[0:1], v[0:1], 2, s[4:5]
	s_lshl_b64 s[6:7], s[6:7], 2
	v_lshl_add_u64 v[2:3], v[2:3], 2, s[4:5]
	v_lshl_add_u64 v[8:9], v[8:9], 2, s[4:5]
	v_lshl_add_u64 v[10:11], v[10:11], 2, s[4:5]
	v_lshl_add_u64 v[0:1], v[0:1], 0, s[6:7]
	v_mov_b32_e32 v19, v129
	v_lshl_add_u64 v[2:3], v[2:3], 0, s[6:7]
	v_lshl_add_u64 v[8:9], v[8:9], 0, s[6:7]
	v_lshl_add_u64 v[10:11], v[10:11], 0, s[6:7]
	v_lshl_add_u64 v[0:1], v[0:1], 0, v[18:19]
	v_lshl_add_u64 v[4:5], v[2:3], 0, v[18:19]
	v_lshl_add_u64 v[8:9], v[8:9], 0, v[18:19]
	v_lshl_add_u64 v[12:13], v[10:11], 0, v[18:19]
	global_load_dwordx4 v[0:3], v[0:1], off nt
	s_nop 0
	global_load_dwordx4 v[4:7], v[4:5], off nt
	s_nop 0
	global_load_dwordx4 v[8:11], v[8:9], off nt
	s_nop 0
	global_load_dwordx4 v[12:15], v[12:13], off nt
